# q/k in-projection epilogue hand-written: QK-RMSNorm + axial rotary with all eight row passes' LDS and table loads in flight (same arithmetic), replaces the serialized compiler loop
# speedup vs baseline: 1.1296x; 1.0150x over previous
.LBB0_280:
	s_cmp_eq_u32 s42, 2
	s_cselect_b32 s39, 1.0, 0x3e38aa3b
	s_cselect_b64 s[8:9], -1, 0
	v_readlane_b32 s76, v207, 20
	v_readlane_b32 s77, v207, 21
	v_readlane_b32 s78, v207, 22
	v_readlane_b32 s79, v207, 23
	s_cmp_eq_u32 s42, 2
	s_cselect_b32 s0, s78, s76
	s_cselect_b32 s1, s79, s77
	s_lshl_b32 s2, s50, 8
	s_add_u32 s0, s0, s2
	s_addc_u32 s1, s1, 0
	v_and_b32_e32 v249, 7, v138
	v_lshlrev_b32_e32 v249, 5, v249
	v_xor_b32_e32 v255, 64, v249
	global_load_dwordx4 v[208:211], v249, s[0:1]
	global_load_dwordx4 v[212:215], v249, s[0:1] offset:16
	global_load_dwordx4 v[216:219], v255, s[0:1]
	global_load_dwordx4 v[220:223], v255, s[0:1] offset:16
	v_lshrrev_b32_e32 v228, 4, v138
	v_and_b32_e32 v229, 15, v138
	v_lshlrev_b32_e32 v229, 5, v229
	s_movk_i32 s2, 0x210
	v_mul_lo_u32 v230, v228, s2
	v_add_u32_e32 v237, v230, v229
	v_xor_b32_e32 v229, 64, v229
	v_add_u32_e32 v238, v230, v229
	v_mbcnt_lo_u32_b32 v231, -1, 0
	v_mbcnt_hi_u32_b32 v231, -1, v231
	v_xor_b32_e32 v252, 1, v231
	v_lshlrev_b32_e32 v252, 2, v252
	v_xor_b32_e32 v253, 2, v231
	v_lshlrev_b32_e32 v253, 2, v253
	v_xor_b32_e32 v254, 4, v231
	v_lshlrev_b32_e32 v254, 2, v254
	s_and_b64 vcc, exec, s[16:17]
	s_cbranch_vccz .Lqk_ctxaddr
	s_lshr_b32 s2, s57, 13
	s_and_b32 s3, s57, 0x1fff
	s_and_b64 vcc, exec, s[8:9]
	s_cbranch_vccnz .Lqk_lat_k
	s_lshl_b32 s2, s2, 2
	s_lshl_b32 s36, s42, 1
	s_add_u32 s2, s2, s36
	s_lshl_b32 s2, s2, 13
	s_add_u32 s2, s2, s3
	s_lshl_b32 s36, s2, 7
	s_add_u32 s36, s36, 0x6bc0000
	s_mov_b32 s38, 0x100000
	s_branch .Lqk_addr_done
.Lqk_lat_k:
	s_lshl_b32 s2, s2, 1
	s_mul_i32 s2, s2, 0x2100
	s_add_u32 s2, s2, s3
	s_addk_i32 s2, 0x100
	s_lshl_b32 s36, s2, 7
	s_add_u32 s36, s36, 0x7400000
	s_mov_b32 s38, 0x108000
	s_branch .Lqk_addr_done
.Lqk_ctxaddr:
	s_add_i32 s2, s57, 0xffffc000
	s_and_b32 s3, s2, 0xff
	s_lshr_b32 s2, s2, 8
	s_and_b64 vcc, exec, s[8:9]
	s_cbranch_vccnz .Lqk_ctx_k
	s_lshl_b32 s2, s2, 2
	s_lshl_b32 s36, s42, 1
	s_add_u32 s2, s2, s36
	s_lshl_b32 s2, s2, 8
	s_add_u32 s2, s2, s3
	s_lshl_b32 s36, s2, 7
	s_add_u32 s36, s36, 0x73c0000
	s_mov_b32 s38, 0x8000
	s_branch .Lqk_addr_done
.Lqk_ctx_k:
	s_lshl_b32 s2, s2, 1
	s_mul_i32 s2, s2, 0x2100
	s_add_u32 s2, s2, s3
	s_lshl_b32 s36, s2, 7
	s_add_u32 s36, s36, 0x7400000
	s_mov_b32 s38, 0x108000
.Lqk_addr_done:
	s_add_u32 s36, s94, s36
	s_addc_u32 s37, s95, 0
	v_bfe_u32 v229, v138, 3, 1
	v_mul_lo_u32 v229, v229, s38
	v_and_b32_e32 v230, 7, v138
	v_lshlrev_b32_e32 v230, 4, v230
	v_lshl_add_u32 v230, v228, 7, v230
	v_add_u32_e32 v236, v229, v230
	s_add_u32 s20, s94, 0x16000
	s_addc_u32 s21, s95, 0
	s_and_b32 s3, s57, 0x1fff
	s_lshr_b32 s3, s3, 6
	s_lshl_b32 s3, s3, 6
	v_and_b32_e32 v229, 1, v138
	v_lshlrev_b32_e32 v229, 5, v229
	v_lshl_add_u32 v250, v228, 6, v229
	v_add_u32_e32 v250, 0x4000, v250
	v_add_u32_e32 v251, s3, v229
	v_and_b32_e32 v230, 4, v138
	v_cmp_ne_u32_e64 s[2:3], 0, v230
	v_mov_b32_e32 v231, 0x2000
	v_mov_b32_e32 v232, 0x1000
	v_cndmask_b32_e64 v248, v231, v232, s[2:3]
	v_and_b32_e32 v230, 2, v138
	v_cmp_eq_u32_e64 s[40:41], 0, v230
	ds_read_b128 v[0:3], v237 offset:0
	ds_read_b128 v[4:7], v237 offset:16
	ds_read_b128 v[32:35], v238 offset:0
	ds_read_b128 v[36:39], v238 offset:16
	ds_read_b128 v[8:11], v237 offset:8448
	ds_read_b128 v[12:15], v237 offset:8464
	ds_read_b128 v[40:43], v238 offset:8448
	ds_read_b128 v[44:47], v238 offset:8464
	ds_read_b128 v[16:19], v237 offset:16896
	ds_read_b128 v[20:23], v237 offset:16912
	ds_read_b128 v[48:51], v238 offset:16896
	ds_read_b128 v[52:55], v238 offset:16912
	ds_read_b128 v[24:27], v237 offset:25344
	ds_read_b128 v[28:31], v237 offset:25360
	ds_read_b128 v[56:59], v238 offset:25344
	ds_read_b128 v[60:63], v238 offset:25360
	s_and_b64 vcc, exec, s[16:17]
	s_cbranch_vccz .Lqk_norope_ld0
	v_add_u32_e32 v229, 0, v250
	v_add_u32_e32 v230, 0, v251
	v_cndmask_b32_e64 v239, v230, v229, s[2:3]
	v_add_u32_e32 v231, v239, v248
	global_load_dwordx4 v[64:67], v239, s[20:21]
	global_load_dwordx4 v[68:71], v239, s[20:21] offset:16
	global_load_dwordx4 v[176:179], v231, s[20:21]
	global_load_dwordx4 v[180:183], v231, s[20:21] offset:16
	v_add_u32_e32 v229, 1024, v250
	v_add_u32_e32 v230, 0, v251
	v_cndmask_b32_e64 v239, v230, v229, s[2:3]
	v_add_u32_e32 v231, v239, v248
	global_load_dwordx4 v[72:75], v239, s[20:21]
	global_load_dwordx4 v[76:79], v239, s[20:21] offset:16
	global_load_dwordx4 v[184:187], v231, s[20:21]
	global_load_dwordx4 v[188:191], v231, s[20:21] offset:16
	v_add_u32_e32 v229, 2048, v250
	v_add_u32_e32 v230, 0, v251
	v_cndmask_b32_e64 v239, v230, v229, s[2:3]
	v_add_u32_e32 v231, v239, v248
	global_load_dwordx4 v[80:83], v239, s[20:21]
	global_load_dwordx4 v[84:87], v239, s[20:21] offset:16
	global_load_dwordx4 v[192:195], v231, s[20:21]
	global_load_dwordx4 v[196:199], v231, s[20:21] offset:16
	v_add_u32_e32 v229, 3072, v250
	v_add_u32_e32 v230, 0, v251
	v_cndmask_b32_e64 v239, v230, v229, s[2:3]
	v_add_u32_e32 v231, v239, v248
	global_load_dwordx4 v[88:91], v239, s[20:21]
	global_load_dwordx4 v[92:95], v239, s[20:21] offset:16
	global_load_dwordx4 v[240:243], v231, s[20:21]
	global_load_dwordx4 v[244:247], v231, s[20:21] offset:16
.Lqk_norope_ld0:
	s_waitcnt lgkmcnt(14)
	v_mul_f32_e32 v228, v0, v0
	v_mul_f32_e32 v229, v1, v1
	v_mul_f32_e32 v230, v2, v2
	v_mul_f32_e32 v231, v3, v3
	v_mul_f32_e32 v232, v4, v4
	v_mul_f32_e32 v233, v5, v5
	v_mul_f32_e32 v234, v6, v6
	v_mul_f32_e32 v235, v7, v7
	v_add_f32_e32 v224, v228, v229
	v_add_f32_e32 v224, v224, v230
	v_add_f32_e32 v224, v224, v231
	v_add_f32_e32 v224, v224, v232
	v_add_f32_e32 v224, v224, v233
	v_add_f32_e32 v224, v224, v234
	v_add_f32_e32 v224, v224, v235
	s_waitcnt lgkmcnt(10)
	v_mul_f32_e32 v228, v8, v8
	v_mul_f32_e32 v229, v9, v9
	v_mul_f32_e32 v230, v10, v10
	v_mul_f32_e32 v231, v11, v11
	v_mul_f32_e32 v232, v12, v12
	v_mul_f32_e32 v233, v13, v13
	v_mul_f32_e32 v234, v14, v14
	v_mul_f32_e32 v235, v15, v15
	v_add_f32_e32 v225, v228, v229
	v_add_f32_e32 v225, v225, v230
	v_add_f32_e32 v225, v225, v231
	v_add_f32_e32 v225, v225, v232
	v_add_f32_e32 v225, v225, v233
	v_add_f32_e32 v225, v225, v234
	v_add_f32_e32 v225, v225, v235
	s_waitcnt lgkmcnt(6)
	v_mul_f32_e32 v228, v16, v16
	v_mul_f32_e32 v229, v17, v17
	v_mul_f32_e32 v230, v18, v18
	v_mul_f32_e32 v231, v19, v19
	v_mul_f32_e32 v232, v20, v20
	v_mul_f32_e32 v233, v21, v21
	v_mul_f32_e32 v234, v22, v22
	v_mul_f32_e32 v235, v23, v23
	v_add_f32_e32 v226, v228, v229
	v_add_f32_e32 v226, v226, v230
	v_add_f32_e32 v226, v226, v231
	v_add_f32_e32 v226, v226, v232
	v_add_f32_e32 v226, v226, v233
	v_add_f32_e32 v226, v226, v234
	v_add_f32_e32 v226, v226, v235
	s_waitcnt lgkmcnt(2)
	v_mul_f32_e32 v228, v24, v24
	v_mul_f32_e32 v229, v25, v25
	v_mul_f32_e32 v230, v26, v26
	v_mul_f32_e32 v231, v27, v27
	v_mul_f32_e32 v232, v28, v28
	v_mul_f32_e32 v233, v29, v29
	v_mul_f32_e32 v234, v30, v30
	v_mul_f32_e32 v235, v31, v31
	v_add_f32_e32 v227, v228, v229
	v_add_f32_e32 v227, v227, v230
	v_add_f32_e32 v227, v227, v231
	v_add_f32_e32 v227, v227, v232
	v_add_f32_e32 v227, v227, v233
	v_add_f32_e32 v227, v227, v234
	v_add_f32_e32 v227, v227, v235
	s_waitcnt lgkmcnt(0)
	ds_bpermute_b32 v228, v252, v224
	ds_bpermute_b32 v229, v252, v225
	ds_bpermute_b32 v230, v252, v226
	ds_bpermute_b32 v231, v252, v227
	s_waitcnt lgkmcnt(3)
	v_add_f32_e32 v224, v224, v228
	s_waitcnt lgkmcnt(2)
	v_add_f32_e32 v225, v225, v229
	s_waitcnt lgkmcnt(1)
	v_add_f32_e32 v226, v226, v230
	s_waitcnt lgkmcnt(0)
	v_add_f32_e32 v227, v227, v231
	ds_bpermute_b32 v228, v253, v224
	ds_bpermute_b32 v229, v253, v225
	ds_bpermute_b32 v230, v253, v226
	ds_bpermute_b32 v231, v253, v227
	s_waitcnt lgkmcnt(3)
	v_add_f32_e32 v224, v224, v228
	s_waitcnt lgkmcnt(2)
	v_add_f32_e32 v225, v225, v229
	s_waitcnt lgkmcnt(1)
	v_add_f32_e32 v226, v226, v230
	s_waitcnt lgkmcnt(0)
	v_add_f32_e32 v227, v227, v231
	ds_bpermute_b32 v228, v254, v224
	ds_bpermute_b32 v229, v254, v225
	ds_bpermute_b32 v230, v254, v226
	ds_bpermute_b32 v231, v254, v227
	s_waitcnt lgkmcnt(3)
	v_add_f32_e32 v224, v224, v228
	s_waitcnt lgkmcnt(2)
	v_add_f32_e32 v225, v225, v229
	s_waitcnt lgkmcnt(1)
	v_add_f32_e32 v226, v226, v230
	s_waitcnt lgkmcnt(0)
	v_add_f32_e32 v227, v227, v231
	s_waitcnt vmcnt(0)
	v_fmamk_f32 v228, v224, 0x3c800000, v139
	v_cmp_gt_f32_e32 vcc, s33, v228
	v_mul_f32_e32 v229, 0x4b800000, v228
	s_nop 0
	v_cndmask_b32_e32 v228, v228, v229, vcc
	v_rsq_f32_e32 v228, v228
	s_nop 0
	v_mul_f32_e32 v229, 0x45800000, v228
	v_cndmask_b32_e32 v228, v228, v229, vcc
	v_mul_f32_e32 v230, v208, v228
	v_mul_f32_e32 v0, v0, v230
	v_mul_f32_e32 v231, v216, v228
	v_mul_f32_e32 v32, v32, v231
	v_mul_f32_e32 v230, v209, v228
	v_mul_f32_e32 v1, v1, v230
	v_mul_f32_e32 v231, v217, v228
	v_mul_f32_e32 v33, v33, v231
	v_mul_f32_e32 v230, v210, v228
	v_mul_f32_e32 v2, v2, v230
	v_mul_f32_e32 v231, v218, v228
	v_mul_f32_e32 v34, v34, v231
	v_mul_f32_e32 v230, v211, v228
	v_mul_f32_e32 v3, v3, v230
	v_mul_f32_e32 v231, v219, v228
	v_mul_f32_e32 v35, v35, v231
	v_mul_f32_e32 v230, v212, v228
	v_mul_f32_e32 v4, v4, v230
	v_mul_f32_e32 v231, v220, v228
	v_mul_f32_e32 v36, v36, v231
	v_mul_f32_e32 v230, v213, v228
	v_mul_f32_e32 v5, v5, v230
	v_mul_f32_e32 v231, v221, v228
	v_mul_f32_e32 v37, v37, v231
	v_mul_f32_e32 v230, v214, v228
	v_mul_f32_e32 v6, v6, v230
	v_mul_f32_e32 v231, v222, v228
	v_mul_f32_e32 v38, v38, v231
	v_mul_f32_e32 v230, v215, v228
	v_mul_f32_e32 v7, v7, v230
	v_mul_f32_e32 v231, v223, v228
	v_mul_f32_e32 v39, v39, v231
	v_fmamk_f32 v228, v225, 0x3c800000, v139
	v_cmp_gt_f32_e32 vcc, s33, v228
	v_mul_f32_e32 v229, 0x4b800000, v228
	s_nop 0
	v_cndmask_b32_e32 v228, v228, v229, vcc
	v_rsq_f32_e32 v228, v228
	s_nop 0
	v_mul_f32_e32 v229, 0x45800000, v228
	v_cndmask_b32_e32 v228, v228, v229, vcc
	v_mul_f32_e32 v230, v208, v228
	v_mul_f32_e32 v8, v8, v230
	v_mul_f32_e32 v231, v216, v228
	v_mul_f32_e32 v40, v40, v231
	v_mul_f32_e32 v230, v209, v228
	v_mul_f32_e32 v9, v9, v230
	v_mul_f32_e32 v231, v217, v228
	v_mul_f32_e32 v41, v41, v231
	v_mul_f32_e32 v230, v210, v228
	v_mul_f32_e32 v10, v10, v230
	v_mul_f32_e32 v231, v218, v228
	v_mul_f32_e32 v42, v42, v231
	v_mul_f32_e32 v230, v211, v228
	v_mul_f32_e32 v11, v11, v230
	v_mul_f32_e32 v231, v219, v228
	v_mul_f32_e32 v43, v43, v231
	v_mul_f32_e32 v230, v212, v228
	v_mul_f32_e32 v12, v12, v230
	v_mul_f32_e32 v231, v220, v228
	v_mul_f32_e32 v44, v44, v231
	v_mul_f32_e32 v230, v213, v228
	v_mul_f32_e32 v13, v13, v230
	v_mul_f32_e32 v231, v221, v228
	v_mul_f32_e32 v45, v45, v231
	v_mul_f32_e32 v230, v214, v228
	v_mul_f32_e32 v14, v14, v230
	v_mul_f32_e32 v231, v222, v228
	v_mul_f32_e32 v46, v46, v231
	v_mul_f32_e32 v230, v215, v228
	v_mul_f32_e32 v15, v15, v230
	v_mul_f32_e32 v231, v223, v228
	v_mul_f32_e32 v47, v47, v231
	v_fmamk_f32 v228, v226, 0x3c800000, v139
	v_cmp_gt_f32_e32 vcc, s33, v228
	v_mul_f32_e32 v229, 0x4b800000, v228
	s_nop 0
	v_cndmask_b32_e32 v228, v228, v229, vcc
	v_rsq_f32_e32 v228, v228
	s_nop 0
	v_mul_f32_e32 v229, 0x45800000, v228
	v_cndmask_b32_e32 v228, v228, v229, vcc
	v_mul_f32_e32 v230, v208, v228
	v_mul_f32_e32 v16, v16, v230
	v_mul_f32_e32 v231, v216, v228
	v_mul_f32_e32 v48, v48, v231
	v_mul_f32_e32 v230, v209, v228
	v_mul_f32_e32 v17, v17, v230
	v_mul_f32_e32 v231, v217, v228
	v_mul_f32_e32 v49, v49, v231
	v_mul_f32_e32 v230, v210, v228
	v_mul_f32_e32 v18, v18, v230
	v_mul_f32_e32 v231, v218, v228
	v_mul_f32_e32 v50, v50, v231
	v_mul_f32_e32 v230, v211, v228
	v_mul_f32_e32 v19, v19, v230
	v_mul_f32_e32 v231, v219, v228
	v_mul_f32_e32 v51, v51, v231
	v_mul_f32_e32 v230, v212, v228
	v_mul_f32_e32 v20, v20, v230
	v_mul_f32_e32 v231, v220, v228
	v_mul_f32_e32 v52, v52, v231
	v_mul_f32_e32 v230, v213, v228
	v_mul_f32_e32 v21, v21, v230
	v_mul_f32_e32 v231, v221, v228
	v_mul_f32_e32 v53, v53, v231
	v_mul_f32_e32 v230, v214, v228
	v_mul_f32_e32 v22, v22, v230
	v_mul_f32_e32 v231, v222, v228
	v_mul_f32_e32 v54, v54, v231
	v_mul_f32_e32 v230, v215, v228
	v_mul_f32_e32 v23, v23, v230
	v_mul_f32_e32 v231, v223, v228
	v_mul_f32_e32 v55, v55, v231
	v_fmamk_f32 v228, v227, 0x3c800000, v139
	v_cmp_gt_f32_e32 vcc, s33, v228
	v_mul_f32_e32 v229, 0x4b800000, v228
	s_nop 0
	v_cndmask_b32_e32 v228, v228, v229, vcc
	v_rsq_f32_e32 v228, v228
	s_nop 0
	v_mul_f32_e32 v229, 0x45800000, v228
	v_cndmask_b32_e32 v228, v228, v229, vcc
	v_mul_f32_e32 v230, v208, v228
	v_mul_f32_e32 v24, v24, v230
	v_mul_f32_e32 v231, v216, v228
	v_mul_f32_e32 v56, v56, v231
	v_mul_f32_e32 v230, v209, v228
	v_mul_f32_e32 v25, v25, v230
	v_mul_f32_e32 v231, v217, v228
	v_mul_f32_e32 v57, v57, v231
	v_mul_f32_e32 v230, v210, v228
	v_mul_f32_e32 v26, v26, v230
	v_mul_f32_e32 v231, v218, v228
	v_mul_f32_e32 v58, v58, v231
	v_mul_f32_e32 v230, v211, v228
	v_mul_f32_e32 v27, v27, v230
	v_mul_f32_e32 v231, v219, v228
	v_mul_f32_e32 v59, v59, v231
	v_mul_f32_e32 v230, v212, v228
	v_mul_f32_e32 v28, v28, v230
	v_mul_f32_e32 v231, v220, v228
	v_mul_f32_e32 v60, v60, v231
	v_mul_f32_e32 v230, v213, v228
	v_mul_f32_e32 v29, v29, v230
	v_mul_f32_e32 v231, v221, v228
	v_mul_f32_e32 v61, v61, v231
	v_mul_f32_e32 v230, v214, v228
	v_mul_f32_e32 v30, v30, v230
	v_mul_f32_e32 v231, v222, v228
	v_mul_f32_e32 v62, v62, v231
	v_mul_f32_e32 v230, v215, v228
	v_mul_f32_e32 v31, v31, v230
	v_mul_f32_e32 v231, v223, v228
	v_mul_f32_e32 v63, v63, v231
	s_and_b64 vcc, exec, s[16:17]
	s_cbranch_vccz .Lqk_norope0
	s_waitcnt vmcnt(0)
	v_mul_f32_e32 v0, v0, v64
	v_cndmask_b32_e64 v230, v32, -v32, s[40:41]
	v_fma_f32 v0, v230, v176, v0
	v_mul_f32_e32 v1, v1, v65
	v_cndmask_b32_e64 v230, v33, -v33, s[40:41]
	v_fma_f32 v1, v230, v177, v1
	v_mul_f32_e32 v2, v2, v66
	v_cndmask_b32_e64 v230, v34, -v34, s[40:41]
	v_fma_f32 v2, v230, v178, v2
	v_mul_f32_e32 v3, v3, v67
	v_cndmask_b32_e64 v230, v35, -v35, s[40:41]
	v_fma_f32 v3, v230, v179, v3
	v_mul_f32_e32 v4, v4, v68
	v_cndmask_b32_e64 v230, v36, -v36, s[40:41]
	v_fma_f32 v4, v230, v180, v4
	v_mul_f32_e32 v5, v5, v69
	v_cndmask_b32_e64 v230, v37, -v37, s[40:41]
	v_fma_f32 v5, v230, v181, v5
	v_mul_f32_e32 v6, v6, v70
	v_cndmask_b32_e64 v230, v38, -v38, s[40:41]
	v_fma_f32 v6, v230, v182, v6
	v_mul_f32_e32 v7, v7, v71
	v_cndmask_b32_e64 v230, v39, -v39, s[40:41]
	v_fma_f32 v7, v230, v183, v7
	v_mul_f32_e32 v8, v8, v72
	v_cndmask_b32_e64 v230, v40, -v40, s[40:41]
	v_fma_f32 v8, v230, v184, v8
	v_mul_f32_e32 v9, v9, v73
	v_cndmask_b32_e64 v230, v41, -v41, s[40:41]
	v_fma_f32 v9, v230, v185, v9
	v_mul_f32_e32 v10, v10, v74
	v_cndmask_b32_e64 v230, v42, -v42, s[40:41]
	v_fma_f32 v10, v230, v186, v10
	v_mul_f32_e32 v11, v11, v75
	v_cndmask_b32_e64 v230, v43, -v43, s[40:41]
	v_fma_f32 v11, v230, v187, v11
	v_mul_f32_e32 v12, v12, v76
	v_cndmask_b32_e64 v230, v44, -v44, s[40:41]
	v_fma_f32 v12, v230, v188, v12
	v_mul_f32_e32 v13, v13, v77
	v_cndmask_b32_e64 v230, v45, -v45, s[40:41]
	v_fma_f32 v13, v230, v189, v13
	v_mul_f32_e32 v14, v14, v78
	v_cndmask_b32_e64 v230, v46, -v46, s[40:41]
	v_fma_f32 v14, v230, v190, v14
	v_mul_f32_e32 v15, v15, v79
	v_cndmask_b32_e64 v230, v47, -v47, s[40:41]
	v_fma_f32 v15, v230, v191, v15
	v_mul_f32_e32 v16, v16, v80
	v_cndmask_b32_e64 v230, v48, -v48, s[40:41]
	v_fma_f32 v16, v230, v192, v16
	v_mul_f32_e32 v17, v17, v81
	v_cndmask_b32_e64 v230, v49, -v49, s[40:41]
	v_fma_f32 v17, v230, v193, v17
	v_mul_f32_e32 v18, v18, v82
	v_cndmask_b32_e64 v230, v50, -v50, s[40:41]
	v_fma_f32 v18, v230, v194, v18
	v_mul_f32_e32 v19, v19, v83
	v_cndmask_b32_e64 v230, v51, -v51, s[40:41]
	v_fma_f32 v19, v230, v195, v19
	v_mul_f32_e32 v20, v20, v84
	v_cndmask_b32_e64 v230, v52, -v52, s[40:41]
	v_fma_f32 v20, v230, v196, v20
	v_mul_f32_e32 v21, v21, v85
	v_cndmask_b32_e64 v230, v53, -v53, s[40:41]
	v_fma_f32 v21, v230, v197, v21
	v_mul_f32_e32 v22, v22, v86
	v_cndmask_b32_e64 v230, v54, -v54, s[40:41]
	v_fma_f32 v22, v230, v198, v22
	v_mul_f32_e32 v23, v23, v87
	v_cndmask_b32_e64 v230, v55, -v55, s[40:41]
	v_fma_f32 v23, v230, v199, v23
	v_mul_f32_e32 v24, v24, v88
	v_cndmask_b32_e64 v230, v56, -v56, s[40:41]
	v_fma_f32 v24, v230, v240, v24
	v_mul_f32_e32 v25, v25, v89
	v_cndmask_b32_e64 v230, v57, -v57, s[40:41]
	v_fma_f32 v25, v230, v241, v25
	v_mul_f32_e32 v26, v26, v90
	v_cndmask_b32_e64 v230, v58, -v58, s[40:41]
	v_fma_f32 v26, v230, v242, v26
	v_mul_f32_e32 v27, v27, v91
	v_cndmask_b32_e64 v230, v59, -v59, s[40:41]
	v_fma_f32 v27, v230, v243, v27
	v_mul_f32_e32 v28, v28, v92
	v_cndmask_b32_e64 v230, v60, -v60, s[40:41]
	v_fma_f32 v28, v230, v244, v28
	v_mul_f32_e32 v29, v29, v93
	v_cndmask_b32_e64 v230, v61, -v61, s[40:41]
	v_fma_f32 v29, v230, v245, v29
	v_mul_f32_e32 v30, v30, v94
	v_cndmask_b32_e64 v230, v62, -v62, s[40:41]
	v_fma_f32 v30, v230, v246, v30
	v_mul_f32_e32 v31, v31, v95
	v_cndmask_b32_e64 v230, v63, -v63, s[40:41]
	v_fma_f32 v31, v230, v247, v31
.Lqk_norope0:
	v_mul_f32_e32 v0, s39, v0
	v_mul_f32_e32 v1, s39, v1
	v_mul_f32_e32 v2, s39, v2
	v_mul_f32_e32 v3, s39, v3
	v_mul_f32_e32 v4, s39, v4
	v_mul_f32_e32 v5, s39, v5
	v_mul_f32_e32 v6, s39, v6
	v_mul_f32_e32 v7, s39, v7
	v_cvt_pk_bf16_f32 v32, v0, v1
	v_cvt_pk_bf16_f32 v33, v2, v3
	v_cvt_pk_bf16_f32 v34, v4, v5
	v_cvt_pk_bf16_f32 v35, v6, v7
	v_add_u32_e32 v232, 0, v236
	global_store_dwordx4 v232, v[32:35], s[36:37]
	v_mul_f32_e32 v8, s39, v8
	v_mul_f32_e32 v9, s39, v9
	v_mul_f32_e32 v10, s39, v10
	v_mul_f32_e32 v11, s39, v11
	v_mul_f32_e32 v12, s39, v12
	v_mul_f32_e32 v13, s39, v13
	v_mul_f32_e32 v14, s39, v14
	v_mul_f32_e32 v15, s39, v15
	v_cvt_pk_bf16_f32 v40, v8, v9
	v_cvt_pk_bf16_f32 v41, v10, v11
	v_cvt_pk_bf16_f32 v42, v12, v13
	v_cvt_pk_bf16_f32 v43, v14, v15
	v_add_u32_e32 v232, 2048, v236
	global_store_dwordx4 v232, v[40:43], s[36:37]
	v_mul_f32_e32 v16, s39, v16
	v_mul_f32_e32 v17, s39, v17
	v_mul_f32_e32 v18, s39, v18
	v_mul_f32_e32 v19, s39, v19
	v_mul_f32_e32 v20, s39, v20
	v_mul_f32_e32 v21, s39, v21
	v_mul_f32_e32 v22, s39, v22
	v_mul_f32_e32 v23, s39, v23
	v_cvt_pk_bf16_f32 v48, v16, v17
	v_cvt_pk_bf16_f32 v49, v18, v19
	v_cvt_pk_bf16_f32 v50, v20, v21
	v_cvt_pk_bf16_f32 v51, v22, v23
	v_add_u32_e32 v232, 4096, v236
	global_store_dwordx4 v232, v[48:51], s[36:37]
	v_mul_f32_e32 v24, s39, v24
	v_mul_f32_e32 v25, s39, v25
	v_mul_f32_e32 v26, s39, v26
	v_mul_f32_e32 v27, s39, v27
	v_mul_f32_e32 v28, s39, v28
	v_mul_f32_e32 v29, s39, v29
	v_mul_f32_e32 v30, s39, v30
	v_mul_f32_e32 v31, s39, v31
	v_cvt_pk_bf16_f32 v56, v24, v25
	v_cvt_pk_bf16_f32 v57, v26, v27
	v_cvt_pk_bf16_f32 v58, v28, v29
	v_cvt_pk_bf16_f32 v59, v30, v31
	v_add_u32_e32 v232, 6144, v236
	global_store_dwordx4 v232, v[56:59], s[36:37]
	ds_read_b128 v[0:3], v237 offset:33792
	ds_read_b128 v[4:7], v237 offset:33808
	ds_read_b128 v[32:35], v238 offset:33792
	ds_read_b128 v[36:39], v238 offset:33808
	ds_read_b128 v[8:11], v237 offset:42240
	ds_read_b128 v[12:15], v237 offset:42256
	ds_read_b128 v[40:43], v238 offset:42240
	ds_read_b128 v[44:47], v238 offset:42256
	ds_read_b128 v[16:19], v237 offset:50688
	ds_read_b128 v[20:23], v237 offset:50704
	ds_read_b128 v[48:51], v238 offset:50688
	ds_read_b128 v[52:55], v238 offset:50704
	ds_read_b128 v[24:27], v237 offset:59136
	ds_read_b128 v[28:31], v237 offset:59152
	ds_read_b128 v[56:59], v238 offset:59136
	ds_read_b128 v[60:63], v238 offset:59152
	s_and_b64 vcc, exec, s[16:17]
	s_cbranch_vccz .Lqk_norope_ld1
	v_add_u32_e32 v229, 0, v250
	v_add_u32_e32 v230, 64, v251
	v_cndmask_b32_e64 v239, v230, v229, s[2:3]
	v_add_u32_e32 v231, v239, v248
	global_load_dwordx4 v[64:67], v239, s[20:21]
	global_load_dwordx4 v[68:71], v239, s[20:21] offset:16
	global_load_dwordx4 v[176:179], v231, s[20:21]
	global_load_dwordx4 v[180:183], v231, s[20:21] offset:16
	v_add_u32_e32 v229, 1024, v250
	v_add_u32_e32 v230, 64, v251
	v_cndmask_b32_e64 v239, v230, v229, s[2:3]
	v_add_u32_e32 v231, v239, v248
	global_load_dwordx4 v[72:75], v239, s[20:21]
	global_load_dwordx4 v[76:79], v239, s[20:21] offset:16
	global_load_dwordx4 v[184:187], v231, s[20:21]
	global_load_dwordx4 v[188:191], v231, s[20:21] offset:16
	v_add_u32_e32 v229, 2048, v250
	v_add_u32_e32 v230, 64, v251
	v_cndmask_b32_e64 v239, v230, v229, s[2:3]
	v_add_u32_e32 v231, v239, v248
	global_load_dwordx4 v[80:83], v239, s[20:21]
	global_load_dwordx4 v[84:87], v239, s[20:21] offset:16
	global_load_dwordx4 v[192:195], v231, s[20:21]
	global_load_dwordx4 v[196:199], v231, s[20:21] offset:16
	v_add_u32_e32 v229, 3072, v250
	v_add_u32_e32 v230, 64, v251
	v_cndmask_b32_e64 v239, v230, v229, s[2:3]
	v_add_u32_e32 v231, v239, v248
	global_load_dwordx4 v[88:91], v239, s[20:21]
	global_load_dwordx4 v[92:95], v239, s[20:21] offset:16
	global_load_dwordx4 v[240:243], v231, s[20:21]
	global_load_dwordx4 v[244:247], v231, s[20:21] offset:16
.Lqk_norope_ld1:
	s_waitcnt lgkmcnt(14)
	v_mul_f32_e32 v228, v0, v0
	v_mul_f32_e32 v229, v1, v1
	v_mul_f32_e32 v230, v2, v2
	v_mul_f32_e32 v231, v3, v3
	v_mul_f32_e32 v232, v4, v4
	v_mul_f32_e32 v233, v5, v5
	v_mul_f32_e32 v234, v6, v6
	v_mul_f32_e32 v235, v7, v7
	v_add_f32_e32 v224, v228, v229
	v_add_f32_e32 v224, v224, v230
	v_add_f32_e32 v224, v224, v231
	v_add_f32_e32 v224, v224, v232
	v_add_f32_e32 v224, v224, v233
	v_add_f32_e32 v224, v224, v234
	v_add_f32_e32 v224, v224, v235
	s_waitcnt lgkmcnt(10)
	v_mul_f32_e32 v228, v8, v8
	v_mul_f32_e32 v229, v9, v9
	v_mul_f32_e32 v230, v10, v10
	v_mul_f32_e32 v231, v11, v11
	v_mul_f32_e32 v232, v12, v12
	v_mul_f32_e32 v233, v13, v13
	v_mul_f32_e32 v234, v14, v14
	v_mul_f32_e32 v235, v15, v15
	v_add_f32_e32 v225, v228, v229
	v_add_f32_e32 v225, v225, v230
	v_add_f32_e32 v225, v225, v231
	v_add_f32_e32 v225, v225, v232
	v_add_f32_e32 v225, v225, v233
	v_add_f32_e32 v225, v225, v234
	v_add_f32_e32 v225, v225, v235
	s_waitcnt lgkmcnt(6)
	v_mul_f32_e32 v228, v16, v16
	v_mul_f32_e32 v229, v17, v17
	v_mul_f32_e32 v230, v18, v18
	v_mul_f32_e32 v231, v19, v19
	v_mul_f32_e32 v232, v20, v20
	v_mul_f32_e32 v233, v21, v21
	v_mul_f32_e32 v234, v22, v22
	v_mul_f32_e32 v235, v23, v23
	v_add_f32_e32 v226, v228, v229
	v_add_f32_e32 v226, v226, v230
	v_add_f32_e32 v226, v226, v231
	v_add_f32_e32 v226, v226, v232
	v_add_f32_e32 v226, v226, v233
	v_add_f32_e32 v226, v226, v234
	v_add_f32_e32 v226, v226, v235
	s_waitcnt lgkmcnt(2)
	v_mul_f32_e32 v228, v24, v24
	v_mul_f32_e32 v229, v25, v25
	v_mul_f32_e32 v230, v26, v26
	v_mul_f32_e32 v231, v27, v27
	v_mul_f32_e32 v232, v28, v28
	v_mul_f32_e32 v233, v29, v29
	v_mul_f32_e32 v234, v30, v30
	v_mul_f32_e32 v235, v31, v31
	v_add_f32_e32 v227, v228, v229
	v_add_f32_e32 v227, v227, v230
	v_add_f32_e32 v227, v227, v231
	v_add_f32_e32 v227, v227, v232
	v_add_f32_e32 v227, v227, v233
	v_add_f32_e32 v227, v227, v234
	v_add_f32_e32 v227, v227, v235
	s_waitcnt lgkmcnt(0)
	ds_bpermute_b32 v228, v252, v224
	ds_bpermute_b32 v229, v252, v225
	ds_bpermute_b32 v230, v252, v226
	ds_bpermute_b32 v231, v252, v227
	s_waitcnt lgkmcnt(3)
	v_add_f32_e32 v224, v224, v228
	s_waitcnt lgkmcnt(2)
	v_add_f32_e32 v225, v225, v229
	s_waitcnt lgkmcnt(1)
	v_add_f32_e32 v226, v226, v230
	s_waitcnt lgkmcnt(0)
	v_add_f32_e32 v227, v227, v231
	ds_bpermute_b32 v228, v253, v224
	ds_bpermute_b32 v229, v253, v225
	ds_bpermute_b32 v230, v253, v226
	ds_bpermute_b32 v231, v253, v227
	s_waitcnt lgkmcnt(3)
	v_add_f32_e32 v224, v224, v228
	s_waitcnt lgkmcnt(2)
	v_add_f32_e32 v225, v225, v229
	s_waitcnt lgkmcnt(1)
	v_add_f32_e32 v226, v226, v230
	s_waitcnt lgkmcnt(0)
	v_add_f32_e32 v227, v227, v231
	ds_bpermute_b32 v228, v254, v224
	ds_bpermute_b32 v229, v254, v225
	ds_bpermute_b32 v230, v254, v226
	ds_bpermute_b32 v231, v254, v227
	s_waitcnt lgkmcnt(3)
	v_add_f32_e32 v224, v224, v228
	s_waitcnt lgkmcnt(2)
	v_add_f32_e32 v225, v225, v229
	s_waitcnt lgkmcnt(1)
	v_add_f32_e32 v226, v226, v230
	s_waitcnt lgkmcnt(0)
	v_add_f32_e32 v227, v227, v231
	v_fmamk_f32 v228, v224, 0x3c800000, v139
	v_cmp_gt_f32_e32 vcc, s33, v228
	v_mul_f32_e32 v229, 0x4b800000, v228
	s_nop 0
	v_cndmask_b32_e32 v228, v228, v229, vcc
	v_rsq_f32_e32 v228, v228
	s_nop 0
	v_mul_f32_e32 v229, 0x45800000, v228
	v_cndmask_b32_e32 v228, v228, v229, vcc
	v_mul_f32_e32 v230, v208, v228
	v_mul_f32_e32 v0, v0, v230
	v_mul_f32_e32 v231, v216, v228
	v_mul_f32_e32 v32, v32, v231
	v_mul_f32_e32 v230, v209, v228
	v_mul_f32_e32 v1, v1, v230
	v_mul_f32_e32 v231, v217, v228
	v_mul_f32_e32 v33, v33, v231
	v_mul_f32_e32 v230, v210, v228
	v_mul_f32_e32 v2, v2, v230
	v_mul_f32_e32 v231, v218, v228
	v_mul_f32_e32 v34, v34, v231
	v_mul_f32_e32 v230, v211, v228
	v_mul_f32_e32 v3, v3, v230
	v_mul_f32_e32 v231, v219, v228
	v_mul_f32_e32 v35, v35, v231
	v_mul_f32_e32 v230, v212, v228
	v_mul_f32_e32 v4, v4, v230
	v_mul_f32_e32 v231, v220, v228
	v_mul_f32_e32 v36, v36, v231
	v_mul_f32_e32 v230, v213, v228
	v_mul_f32_e32 v5, v5, v230
	v_mul_f32_e32 v231, v221, v228
	v_mul_f32_e32 v37, v37, v231
	v_mul_f32_e32 v230, v214, v228
	v_mul_f32_e32 v6, v6, v230
	v_mul_f32_e32 v231, v222, v228
	v_mul_f32_e32 v38, v38, v231
	v_mul_f32_e32 v230, v215, v228
	v_mul_f32_e32 v7, v7, v230
	v_mul_f32_e32 v231, v223, v228
	v_mul_f32_e32 v39, v39, v231
	v_fmamk_f32 v228, v225, 0x3c800000, v139
	v_cmp_gt_f32_e32 vcc, s33, v228
	v_mul_f32_e32 v229, 0x4b800000, v228
	s_nop 0
	v_cndmask_b32_e32 v228, v228, v229, vcc
	v_rsq_f32_e32 v228, v228
	s_nop 0
	v_mul_f32_e32 v229, 0x45800000, v228
	v_cndmask_b32_e32 v228, v228, v229, vcc
	v_mul_f32_e32 v230, v208, v228
	v_mul_f32_e32 v8, v8, v230
	v_mul_f32_e32 v231, v216, v228
	v_mul_f32_e32 v40, v40, v231
	v_mul_f32_e32 v230, v209, v228
	v_mul_f32_e32 v9, v9, v230
	v_mul_f32_e32 v231, v217, v228
	v_mul_f32_e32 v41, v41, v231
	v_mul_f32_e32 v230, v210, v228
	v_mul_f32_e32 v10, v10, v230
	v_mul_f32_e32 v231, v218, v228
	v_mul_f32_e32 v42, v42, v231
	v_mul_f32_e32 v230, v211, v228
	v_mul_f32_e32 v11, v11, v230
	v_mul_f32_e32 v231, v219, v228
	v_mul_f32_e32 v43, v43, v231
	v_mul_f32_e32 v230, v212, v228
	v_mul_f32_e32 v12, v12, v230
	v_mul_f32_e32 v231, v220, v228
	v_mul_f32_e32 v44, v44, v231
	v_mul_f32_e32 v230, v213, v228
	v_mul_f32_e32 v13, v13, v230
	v_mul_f32_e32 v231, v221, v228
	v_mul_f32_e32 v45, v45, v231
	v_mul_f32_e32 v230, v214, v228
	v_mul_f32_e32 v14, v14, v230
	v_mul_f32_e32 v231, v222, v228
	v_mul_f32_e32 v46, v46, v231
	v_mul_f32_e32 v230, v215, v228
	v_mul_f32_e32 v15, v15, v230
	v_mul_f32_e32 v231, v223, v228
	v_mul_f32_e32 v47, v47, v231
	v_fmamk_f32 v228, v226, 0x3c800000, v139
	v_cmp_gt_f32_e32 vcc, s33, v228
	v_mul_f32_e32 v229, 0x4b800000, v228
	s_nop 0
	v_cndmask_b32_e32 v228, v228, v229, vcc
	v_rsq_f32_e32 v228, v228
	s_nop 0
	v_mul_f32_e32 v229, 0x45800000, v228
	v_cndmask_b32_e32 v228, v228, v229, vcc
	v_mul_f32_e32 v230, v208, v228
	v_mul_f32_e32 v16, v16, v230
	v_mul_f32_e32 v231, v216, v228
	v_mul_f32_e32 v48, v48, v231
	v_mul_f32_e32 v230, v209, v228
	v_mul_f32_e32 v17, v17, v230
	v_mul_f32_e32 v231, v217, v228
	v_mul_f32_e32 v49, v49, v231
	v_mul_f32_e32 v230, v210, v228
	v_mul_f32_e32 v18, v18, v230
	v_mul_f32_e32 v231, v218, v228
	v_mul_f32_e32 v50, v50, v231
	v_mul_f32_e32 v230, v211, v228
	v_mul_f32_e32 v19, v19, v230
	v_mul_f32_e32 v231, v219, v228
	v_mul_f32_e32 v51, v51, v231
	v_mul_f32_e32 v230, v212, v228
	v_mul_f32_e32 v20, v20, v230
	v_mul_f32_e32 v231, v220, v228
	v_mul_f32_e32 v52, v52, v231
	v_mul_f32_e32 v230, v213, v228
	v_mul_f32_e32 v21, v21, v230
	v_mul_f32_e32 v231, v221, v228
	v_mul_f32_e32 v53, v53, v231
	v_mul_f32_e32 v230, v214, v228
	v_mul_f32_e32 v22, v22, v230
	v_mul_f32_e32 v231, v222, v228
	v_mul_f32_e32 v54, v54, v231
	v_mul_f32_e32 v230, v215, v228
	v_mul_f32_e32 v23, v23, v230
	v_mul_f32_e32 v231, v223, v228
	v_mul_f32_e32 v55, v55, v231
	v_fmamk_f32 v228, v227, 0x3c800000, v139
	v_cmp_gt_f32_e32 vcc, s33, v228
	v_mul_f32_e32 v229, 0x4b800000, v228
	s_nop 0
	v_cndmask_b32_e32 v228, v228, v229, vcc
	v_rsq_f32_e32 v228, v228
	s_nop 0
	v_mul_f32_e32 v229, 0x45800000, v228
	v_cndmask_b32_e32 v228, v228, v229, vcc
	v_mul_f32_e32 v230, v208, v228
	v_mul_f32_e32 v24, v24, v230
	v_mul_f32_e32 v231, v216, v228
	v_mul_f32_e32 v56, v56, v231
	v_mul_f32_e32 v230, v209, v228
	v_mul_f32_e32 v25, v25, v230
	v_mul_f32_e32 v231, v217, v228
	v_mul_f32_e32 v57, v57, v231
	v_mul_f32_e32 v230, v210, v228
	v_mul_f32_e32 v26, v26, v230
	v_mul_f32_e32 v231, v218, v228
	v_mul_f32_e32 v58, v58, v231
	v_mul_f32_e32 v230, v211, v228
	v_mul_f32_e32 v27, v27, v230
	v_mul_f32_e32 v231, v219, v228
	v_mul_f32_e32 v59, v59, v231
	v_mul_f32_e32 v230, v212, v228
	v_mul_f32_e32 v28, v28, v230
	v_mul_f32_e32 v231, v220, v228
	v_mul_f32_e32 v60, v60, v231
	v_mul_f32_e32 v230, v213, v228
	v_mul_f32_e32 v29, v29, v230
	v_mul_f32_e32 v231, v221, v228
	v_mul_f32_e32 v61, v61, v231
	v_mul_f32_e32 v230, v214, v228
	v_mul_f32_e32 v30, v30, v230
	v_mul_f32_e32 v231, v222, v228
	v_mul_f32_e32 v62, v62, v231
	v_mul_f32_e32 v230, v215, v228
	v_mul_f32_e32 v31, v31, v230
	v_mul_f32_e32 v231, v223, v228
	v_mul_f32_e32 v63, v63, v231
	s_and_b64 vcc, exec, s[16:17]
	s_cbranch_vccz .Lqk_norope1
	s_waitcnt vmcnt(0)
	v_mul_f32_e32 v0, v0, v64
	v_cndmask_b32_e64 v230, v32, -v32, s[40:41]
	v_fma_f32 v0, v230, v176, v0
	v_mul_f32_e32 v1, v1, v65
	v_cndmask_b32_e64 v230, v33, -v33, s[40:41]
	v_fma_f32 v1, v230, v177, v1
	v_mul_f32_e32 v2, v2, v66
	v_cndmask_b32_e64 v230, v34, -v34, s[40:41]
	v_fma_f32 v2, v230, v178, v2
	v_mul_f32_e32 v3, v3, v67
	v_cndmask_b32_e64 v230, v35, -v35, s[40:41]
	v_fma_f32 v3, v230, v179, v3
	v_mul_f32_e32 v4, v4, v68
	v_cndmask_b32_e64 v230, v36, -v36, s[40:41]
	v_fma_f32 v4, v230, v180, v4
	v_mul_f32_e32 v5, v5, v69
	v_cndmask_b32_e64 v230, v37, -v37, s[40:41]
	v_fma_f32 v5, v230, v181, v5
	v_mul_f32_e32 v6, v6, v70
	v_cndmask_b32_e64 v230, v38, -v38, s[40:41]
	v_fma_f32 v6, v230, v182, v6
	v_mul_f32_e32 v7, v7, v71
	v_cndmask_b32_e64 v230, v39, -v39, s[40:41]
	v_fma_f32 v7, v230, v183, v7
	v_mul_f32_e32 v8, v8, v72
	v_cndmask_b32_e64 v230, v40, -v40, s[40:41]
	v_fma_f32 v8, v230, v184, v8
	v_mul_f32_e32 v9, v9, v73
	v_cndmask_b32_e64 v230, v41, -v41, s[40:41]
	v_fma_f32 v9, v230, v185, v9
	v_mul_f32_e32 v10, v10, v74
	v_cndmask_b32_e64 v230, v42, -v42, s[40:41]
	v_fma_f32 v10, v230, v186, v10
	v_mul_f32_e32 v11, v11, v75
	v_cndmask_b32_e64 v230, v43, -v43, s[40:41]
	v_fma_f32 v11, v230, v187, v11
	v_mul_f32_e32 v12, v12, v76
	v_cndmask_b32_e64 v230, v44, -v44, s[40:41]
	v_fma_f32 v12, v230, v188, v12
	v_mul_f32_e32 v13, v13, v77
	v_cndmask_b32_e64 v230, v45, -v45, s[40:41]
	v_fma_f32 v13, v230, v189, v13
	v_mul_f32_e32 v14, v14, v78
	v_cndmask_b32_e64 v230, v46, -v46, s[40:41]
	v_fma_f32 v14, v230, v190, v14
	v_mul_f32_e32 v15, v15, v79
	v_cndmask_b32_e64 v230, v47, -v47, s[40:41]
	v_fma_f32 v15, v230, v191, v15
	v_mul_f32_e32 v16, v16, v80
	v_cndmask_b32_e64 v230, v48, -v48, s[40:41]
	v_fma_f32 v16, v230, v192, v16
	v_mul_f32_e32 v17, v17, v81
	v_cndmask_b32_e64 v230, v49, -v49, s[40:41]
	v_fma_f32 v17, v230, v193, v17
	v_mul_f32_e32 v18, v18, v82
	v_cndmask_b32_e64 v230, v50, -v50, s[40:41]
	v_fma_f32 v18, v230, v194, v18
	v_mul_f32_e32 v19, v19, v83
	v_cndmask_b32_e64 v230, v51, -v51, s[40:41]
	v_fma_f32 v19, v230, v195, v19
	v_mul_f32_e32 v20, v20, v84
	v_cndmask_b32_e64 v230, v52, -v52, s[40:41]
	v_fma_f32 v20, v230, v196, v20
	v_mul_f32_e32 v21, v21, v85
	v_cndmask_b32_e64 v230, v53, -v53, s[40:41]
	v_fma_f32 v21, v230, v197, v21
	v_mul_f32_e32 v22, v22, v86
	v_cndmask_b32_e64 v230, v54, -v54, s[40:41]
	v_fma_f32 v22, v230, v198, v22
	v_mul_f32_e32 v23, v23, v87
	v_cndmask_b32_e64 v230, v55, -v55, s[40:41]
	v_fma_f32 v23, v230, v199, v23
	v_mul_f32_e32 v24, v24, v88
	v_cndmask_b32_e64 v230, v56, -v56, s[40:41]
	v_fma_f32 v24, v230, v240, v24
	v_mul_f32_e32 v25, v25, v89
	v_cndmask_b32_e64 v230, v57, -v57, s[40:41]
	v_fma_f32 v25, v230, v241, v25
	v_mul_f32_e32 v26, v26, v90
	v_cndmask_b32_e64 v230, v58, -v58, s[40:41]
	v_fma_f32 v26, v230, v242, v26
	v_mul_f32_e32 v27, v27, v91
	v_cndmask_b32_e64 v230, v59, -v59, s[40:41]
	v_fma_f32 v27, v230, v243, v27
	v_mul_f32_e32 v28, v28, v92
	v_cndmask_b32_e64 v230, v60, -v60, s[40:41]
	v_fma_f32 v28, v230, v244, v28
	v_mul_f32_e32 v29, v29, v93
	v_cndmask_b32_e64 v230, v61, -v61, s[40:41]
	v_fma_f32 v29, v230, v245, v29
	v_mul_f32_e32 v30, v30, v94
	v_cndmask_b32_e64 v230, v62, -v62, s[40:41]
	v_fma_f32 v30, v230, v246, v30
	v_mul_f32_e32 v31, v31, v95
	v_cndmask_b32_e64 v230, v63, -v63, s[40:41]
	v_fma_f32 v31, v230, v247, v31
.Lqk_norope1:
	v_mul_f32_e32 v0, s39, v0
	v_mul_f32_e32 v1, s39, v1
	v_mul_f32_e32 v2, s39, v2
	v_mul_f32_e32 v3, s39, v3
	v_mul_f32_e32 v4, s39, v4
	v_mul_f32_e32 v5, s39, v5
	v_mul_f32_e32 v6, s39, v6
	v_mul_f32_e32 v7, s39, v7
	v_cvt_pk_bf16_f32 v32, v0, v1
	v_cvt_pk_bf16_f32 v33, v2, v3
	v_cvt_pk_bf16_f32 v34, v4, v5
	v_cvt_pk_bf16_f32 v35, v6, v7
	v_add_u32_e32 v232, 8192, v236
	global_store_dwordx4 v232, v[32:35], s[36:37]
	v_mul_f32_e32 v8, s39, v8
	v_mul_f32_e32 v9, s39, v9
	v_mul_f32_e32 v10, s39, v10
	v_mul_f32_e32 v11, s39, v11
	v_mul_f32_e32 v12, s39, v12
	v_mul_f32_e32 v13, s39, v13
	v_mul_f32_e32 v14, s39, v14
	v_mul_f32_e32 v15, s39, v15
	v_cvt_pk_bf16_f32 v40, v8, v9
	v_cvt_pk_bf16_f32 v41, v10, v11
	v_cvt_pk_bf16_f32 v42, v12, v13
	v_cvt_pk_bf16_f32 v43, v14, v15
	v_add_u32_e32 v232, 10240, v236
	global_store_dwordx4 v232, v[40:43], s[36:37]
	v_mul_f32_e32 v16, s39, v16
	v_mul_f32_e32 v17, s39, v17
	v_mul_f32_e32 v18, s39, v18
	v_mul_f32_e32 v19, s39, v19
	v_mul_f32_e32 v20, s39, v20
	v_mul_f32_e32 v21, s39, v21
	v_mul_f32_e32 v22, s39, v22
	v_mul_f32_e32 v23, s39, v23
	v_cvt_pk_bf16_f32 v48, v16, v17
	v_cvt_pk_bf16_f32 v49, v18, v19
	v_cvt_pk_bf16_f32 v50, v20, v21
	v_cvt_pk_bf16_f32 v51, v22, v23
	v_add_u32_e32 v232, 12288, v236
	global_store_dwordx4 v232, v[48:51], s[36:37]
	v_mul_f32_e32 v24, s39, v24
	v_mul_f32_e32 v25, s39, v25
	v_mul_f32_e32 v26, s39, v26
	v_mul_f32_e32 v27, s39, v27
	v_mul_f32_e32 v28, s39, v28
	v_mul_f32_e32 v29, s39, v29
	v_mul_f32_e32 v30, s39, v30
	v_mul_f32_e32 v31, s39, v31
	v_cvt_pk_bf16_f32 v56, v24, v25
	v_cvt_pk_bf16_f32 v57, v26, v27
	v_cvt_pk_bf16_f32 v58, v28, v29
	v_cvt_pk_bf16_f32 v59, v30, v31
	v_add_u32_e32 v232, 14336, v236
	global_store_dwordx4 v232, v[56:59], s[36:37]
	s_branch .LBB0_237
